# speedup vs baseline: 1.0206x; 1.0033x over previous
; template <int EPI, int AMAP, int KOFFMODE, int K>
; __device__ __forceinline__ void gemm_phase(unsigned char* smem, const bf16_t* A, int lda, const bf16_t* Bt, int NT, const EpiArgs& ea) {
;     ...
;         f32x16 acc[4][2];
; #pragma unroll
;         for (int i = 0; i < 4; ++i)
; #pragma unroll
;             for (int j = 0; j < 2; ++j)
; #pragma unroll
;                 for (int r = 0; r < 16; ++r) acc[i][j][r] = 0.f;
;         for (int kt = 0; kt < nk; ++kt) {
;             if (kt + 1 < nk) GEMM_DMA(m0, n0, kt + 1, cur ^ 1);
;             else if (have_next) GEMM_DMA(m0n, n0n, 0, cur ^ 1);
;             const unsigned char* Ac = smem + cur * STGB + (wm * 128 + l31) * 128;
;             const unsigned char* Bc = smem + cur * STGB + 32768 + (wn * 64 + l31) * 128;
;             bf16x8 fa[2][4], fb[2][2];
;             fb[0][0] = *(const bf16x8*)(Bc + (((0) ^ yz) & 7) * 16);
;             fb[0][1] = *(const bf16x8*)(Bc + 32 * 128 + (((0) ^ yz) & 7) * 16);
; #pragma unroll
;             for (int i = 0; i < 4; ++i) fa[0][i] = *(const bf16x8*)(Ac + i * 32 * 128 + (((0) ^ yz) & 7) * 16);
; #pragma unroll
;             for (int s = 0; s < 4; ++s) {
;                 if (s < 3) {
;                     const int o_ = (((2 * (s + 1)) ^ yz) & 7) * 16;
;                     fb[(s + 1) & 1][0] = *(const bf16x8*)(Bc + o_);
;                     fb[(s + 1) & 1][1] = *(const bf16x8*)(Bc + 32 * 128 + o_);
; #pragma unroll
;                     for (int i = 0; i < 4; ++i) fa[(s + 1) & 1][i] = *(const bf16x8*)(Ac + i * 32 * 128 + o_);
;                 }
; #pragma unroll
;                 for (int i = 0; i < 4; ++i) {
;                     acc[i][0] = __builtin_amdgcn_mfma_f32_32x32x16_bf16(fa[s & 1][i], fb[s & 1][0], acc[i][0], 0, 0, 0);
;                     acc[i][1] = __builtin_amdgcn_mfma_f32_32x32x16_bf16(fa[s & 1][i], fb[s & 1][1], acc[i][1], 0, 0, 0);
;                 }
;                 __builtin_amdgcn_sched_barrier(0);
;             }
;             if (kt + 1 < nk) asm volatile("s_waitcnt vmcnt(0)" ::: "memory");
;             __builtin_amdgcn_s_barrier();
;             cur ^= 1;
;         }
.LBB0_154:
	v_add_u32_e32 v2, s10, v141
	v_ashrrev_i32_e32 v3, 31, v2
	v_lshlrev_b64 v[2:3], 11, v[2:3]
	v_lshl_add_u64 v[136:137], v[134:135], 0, v[2:3]
	v_add_u32_e32 v2, s11, v141
	v_ashrrev_i32_e32 v3, 31, v2
	v_lshlrev_b64 v[2:3], 11, v[2:3]
	v_lshl_add_u64 v[138:139], v[134:135], 0, v[2:3]
	v_mov_b32_e32 v2, 0
	s_mov_b64 s[4:5], 0
	s_mov_b32 s13, s9
	v_mov_b32_e32 v3, v2
	v_mov_b32_e32 v4, v2
	v_mov_b32_e32 v5, v2
	v_mov_b32_e32 v6, v2
	v_mov_b32_e32 v7, v2
	v_mov_b32_e32 v8, v2
	v_mov_b32_e32 v9, v2
	v_mov_b32_e32 v10, v2
	v_mov_b32_e32 v11, v2
	v_mov_b32_e32 v12, v2
	v_mov_b32_e32 v13, v2
	v_mov_b32_e32 v14, v2
	v_mov_b32_e32 v15, v2
	v_mov_b32_e32 v16, v2
	v_mov_b32_e32 v17, v2
	v_mov_b32_e32 v18, v2
	v_mov_b32_e32 v19, v2
	v_mov_b32_e32 v20, v2
	v_mov_b32_e32 v21, v2
	v_mov_b32_e32 v22, v2
	v_mov_b32_e32 v23, v2
	v_mov_b32_e32 v24, v2
	v_mov_b32_e32 v25, v2
	v_mov_b32_e32 v26, v2
	v_mov_b32_e32 v27, v2
	v_mov_b32_e32 v28, v2
	v_mov_b32_e32 v29, v2
	v_mov_b32_e32 v30, v2
	v_mov_b32_e32 v31, v2
	v_mov_b32_e32 v32, v2
	v_mov_b32_e32 v33, v2
	v_mov_b32_e32 v34, v2
	v_mov_b32_e32 v35, v2
	v_mov_b32_e32 v36, v2
	v_mov_b32_e32 v37, v2
	v_mov_b32_e32 v38, v2
	v_mov_b32_e32 v39, v2
	v_mov_b32_e32 v40, v2
	v_mov_b32_e32 v41, v2
	v_mov_b32_e32 v42, v2
	v_mov_b32_e32 v43, v2
	v_mov_b32_e32 v44, v2
	v_mov_b32_e32 v45, v2
	v_mov_b32_e32 v46, v2
	v_mov_b32_e32 v47, v2
	v_mov_b32_e32 v48, v2
	v_mov_b32_e32 v49, v2
	v_mov_b32_e32 v50, v2
	v_mov_b32_e32 v51, v2
	v_mov_b32_e32 v52, v2
	v_mov_b32_e32 v53, v2
	v_mov_b32_e32 v54, v2
	v_mov_b32_e32 v55, v2
	v_mov_b32_e32 v56, v2
	v_mov_b32_e32 v57, v2
	v_mov_b32_e32 v58, v2
	v_mov_b32_e32 v59, v2
	v_mov_b32_e32 v60, v2
	v_mov_b32_e32 v61, v2
	v_mov_b32_e32 v62, v2
	v_mov_b32_e32 v63, v2
	v_mov_b32_e32 v64, v2
	v_mov_b32_e32 v65, v2
	v_mov_b32_e32 v66, v2
	v_mov_b32_e32 v67, v2
	v_mov_b32_e32 v68, v2
	v_mov_b32_e32 v69, v2
	v_mov_b32_e32 v70, v2
	v_mov_b32_e32 v71, v2
	v_mov_b32_e32 v72, v2
	v_mov_b32_e32 v73, v2
	v_mov_b32_e32 v74, v2
	v_mov_b32_e32 v75, v2
	v_mov_b32_e32 v76, v2
	v_mov_b32_e32 v77, v2
	v_mov_b32_e32 v78, v2
	v_mov_b32_e32 v79, v2
	v_mov_b32_e32 v80, v2
	v_mov_b32_e32 v81, v2
	v_mov_b32_e32 v82, v2
	v_mov_b32_e32 v83, v2
	v_mov_b32_e32 v84, v2
	v_mov_b32_e32 v85, v2
	v_mov_b32_e32 v86, v2
	v_mov_b32_e32 v87, v2
	v_mov_b32_e32 v88, v2
	v_mov_b32_e32 v89, v2
	v_mov_b32_e32 v90, v2
	v_mov_b32_e32 v91, v2
	v_mov_b32_e32 v92, v2
	v_mov_b32_e32 v93, v2
	v_mov_b32_e32 v94, v2
	v_mov_b32_e32 v95, v2
	v_mov_b32_e32 v96, v2
	v_mov_b32_e32 v97, v2
	v_mov_b32_e32 v98, v2
	v_mov_b32_e32 v99, v2
	v_mov_b32_e32 v100, v2
	v_mov_b32_e32 v101, v2
	v_mov_b32_e32 v102, v2
	v_mov_b32_e32 v103, v2
	v_mov_b32_e32 v104, v2
	v_mov_b32_e32 v105, v2
	v_mov_b32_e32 v106, v2
	v_mov_b32_e32 v107, v2
	v_mov_b32_e32 v108, v2
	v_mov_b32_e32 v109, v2
	v_mov_b32_e32 v110, v2
	v_mov_b32_e32 v111, v2
	v_mov_b32_e32 v112, v2
	v_mov_b32_e32 v113, v2
	v_mov_b32_e32 v114, v2
	v_mov_b32_e32 v115, v2
	v_mov_b32_e32 v116, v2
	v_mov_b32_e32 v117, v2
	v_mov_b32_e32 v118, v2
	v_mov_b32_e32 v119, v2
	v_mov_b32_e32 v120, v2
	v_mov_b32_e32 v121, v2
	v_mov_b32_e32 v122, v2
	v_mov_b32_e32 v123, v2
	v_mov_b32_e32 v124, v2
	v_mov_b32_e32 v125, v2
	v_mov_b32_e32 v126, v2
	v_mov_b32_e32 v127, v2
	v_mov_b32_e32 v128, v2
	v_mov_b32_e32 v129, v2
	s_mov_b64 s[20:21], 0x2000080
	s_mov_b64 vcc, 0x200080
	s_mov_b64 s[80:81], 0x2020080
	s_mov_b64 s[68:69], 0x220080
	s_mov_b64 s[88:89], 0x2040080
	s_mov_b64 s[92:93], 0x240080
	s_mov_b64 s[62:63], 0x2060080
	s_mov_b64 s[64:65], 0x260080
	s_lshl_b32 s14, s13, 16
	v_add3_u32 v154, s14, v149, v147
	v_add_u32_e32 v154, v154, v150
	ds_read_b128 v[154:157], v154 offset:32768
	v_add3_u32 v158, s14, v149, v147
	v_add_u32_e32 v158, v158, v150
	ds_read_b128 v[158:161], v158 offset:36864
	v_add3_u32 v192, s14, v145, v147
	v_add_u32_e32 v192, v192, v150
	ds_read_b128 v[192:195], v192
	v_add3_u32 v196, s14, v145, v147
	v_add_u32_e32 v196, v196, v150
	ds_read_b128 v[196:199], v196 offset:4096
	v_add3_u32 v200, s14, v145, v147
	v_add_u32_e32 v200, v200, v150
	ds_read_b128 v[200:203], v200 offset:8192
	v_add3_u32 v204, s14, v145, v147
	v_add_u32_e32 v204, v204, v150
	ds_read_b128 v[204:207], v204 offset:12288
.LBB0_155:
	s_mov_b32 s9, s13
	s_lshl_b32 s13, s9, 16
	s_xor_b32 s12, s13, 0x10000
	v_readfirstlane_b32 s14, v142
	s_nop 0
	s_add_u32 s14, s14, s12
	v_add3_u32 v162, s13, v149, v147
	v_add_u32_e32 v162, v162, v151
	ds_read_b128 v[162:165], v162 offset:32768
	v_add3_u32 v208, s13, v149, v147
	v_add_u32_e32 v208, v208, v151
	ds_read_b128 v[208:211], v208 offset:36864
	s_waitcnt lgkmcnt(5)
	v_mfma_f32_32x32x16_bf16 v[114:129], v[192:195], v[154:157], v[114:129]
	v_mfma_f32_32x32x16_bf16 v[98:113], v[192:195], v[158:161], v[98:113]
	s_mov_b32 m0, s14
	v_lshl_add_u64 v[192:193], v[136:137], 0, s[4:5]
	v_lshl_add_u64 v[192:193], v[192:193], 0, s[20:21]
	global_load_lds_dwordx4 v[192:193], off
	s_add_u32 m0, s14, 0x2000
	v_lshl_add_u64 v[192:193], v[136:137], 0, s[4:5]
	v_lshl_add_u64 v[192:193], v[192:193], 0, s[80:81]
	global_load_lds_dwordx4 v[192:193], off
	v_add3_u32 v192, s13, v145, v147
	v_add_u32_e32 v192, v192, v151
	ds_read_b128 v[192:195], v192
	s_waitcnt lgkmcnt(5)
	v_mfma_f32_32x32x16_bf16 v[82:97], v[196:199], v[154:157], v[82:97]
	v_mfma_f32_32x32x16_bf16 v[66:81], v[196:199], v[158:161], v[66:81]
	s_add_u32 m0, s14, 0x4000
	v_lshl_add_u64 v[196:197], v[136:137], 0, s[4:5]
	v_lshl_add_u64 v[196:197], v[196:197], 0, s[88:89]
	global_load_lds_dwordx4 v[196:197], off
	s_add_u32 m0, s14, 0x6000
	v_lshl_add_u64 v[196:197], v[136:137], 0, s[4:5]
	v_lshl_add_u64 v[196:197], v[196:197], 0, s[62:63]
	global_load_lds_dwordx4 v[196:197], off
	v_add3_u32 v196, s13, v145, v147
	v_add_u32_e32 v196, v196, v151
	ds_read_b128 v[196:199], v196 offset:4096
	s_waitcnt lgkmcnt(5)
; template <int EPI, int AMAP, int KOFFMODE, int K>
; __device__ __forceinline__ void gemm_phase(unsigned char* smem, const bf16_t* A, int lda, const bf16_t* Bt, int NT, const EpiArgs& ea) {
;     ...
;         for (int kt = 0; kt < nk; ++kt) {
;             if (kt + 1 < nk) GEMM_DMA(m0, n0, kt + 1, cur ^ 1);
;             else if (have_next) GEMM_DMA(m0n, n0n, 0, cur ^ 1);
;             const unsigned char* Ac = smem + cur * STGB + (wm * 128 + l31) * 128;
;             const unsigned char* Bc = smem + cur * STGB + 32768 + (wn * 64 + l31) * 128;
;             bf16x8 fa[2][4], fb[2][2];
;             fb[0][0] = *(const bf16x8*)(Bc + (((0) ^ yz) & 7) * 16);
;             fb[0][1] = *(const bf16x8*)(Bc + 32 * 128 + (((0) ^ yz) & 7) * 16);
; #pragma unroll
;             for (int i = 0; i < 4; ++i) fa[0][i] = *(const bf16x8*)(Ac + i * 32 * 128 + (((0) ^ yz) & 7) * 16);
; #pragma unroll
;             for (int s = 0; s < 4; ++s) {
;                 if (s < 3) {
;                     const int o_ = (((2 * (s + 1)) ^ yz) & 7) * 16;
;                     fb[(s + 1) & 1][0] = *(const bf16x8*)(Bc + o_);
;                     fb[(s + 1) & 1][1] = *(const bf16x8*)(Bc + 32 * 128 + o_);
; #pragma unroll
;                     for (int i = 0; i < 4; ++i) fa[(s + 1) & 1][i] = *(const bf16x8*)(Ac + i * 32 * 128 + o_);
;                 }
; #pragma unroll
;                 for (int i = 0; i < 4; ++i) {
;                     acc[i][0] = __builtin_amdgcn_mfma_f32_32x32x16_bf16(fa[s & 1][i], fb[s & 1][0], acc[i][0], 0, 0, 0);
;                     acc[i][1] = __builtin_amdgcn_mfma_f32_32x32x16_bf16(fa[s & 1][i], fb[s & 1][1], acc[i][1], 0, 0, 0);
;                 }
;                 __builtin_amdgcn_sched_barrier(0);
;             }
;             if (kt + 1 < nk) asm volatile("s_waitcnt vmcnt(0)" ::: "memory");
;             __builtin_amdgcn_s_barrier();
;             cur ^= 1;
;         }
	v_mfma_f32_32x32x16_bf16 v[50:65], v[200:203], v[154:157], v[50:65]
	v_mfma_f32_32x32x16_bf16 v[34:49], v[200:203], v[158:161], v[34:49]
	s_add_u32 m0, s14, 0x8000
	v_lshl_add_u64 v[200:201], v[138:139], 0, s[4:5]
	v_lshl_add_u64 v[200:201], v[200:201], 0, vcc
	global_load_lds_dwordx4 v[200:201], off
	s_add_u32 m0, s14, 0xa000
	v_lshl_add_u64 v[200:201], v[138:139], 0, s[4:5]
	v_lshl_add_u64 v[200:201], v[200:201], 0, s[68:69]
	global_load_lds_dwordx4 v[200:201], off
	v_add3_u32 v200, s13, v145, v147
	v_add_u32_e32 v200, v200, v151
	ds_read_b128 v[200:203], v200 offset:8192
	s_waitcnt lgkmcnt(5)
	v_mfma_f32_32x32x16_bf16 v[18:33], v[204:207], v[154:157], v[18:33]
	v_mfma_f32_32x32x16_bf16 v[2:17], v[204:207], v[158:161], v[2:17]
	s_add_u32 m0, s14, 0xc000
	v_lshl_add_u64 v[204:205], v[138:139], 0, s[4:5]
	v_lshl_add_u64 v[204:205], v[204:205], 0, s[92:93]
	global_load_lds_dwordx4 v[204:205], off
	s_add_u32 m0, s14, 0xe000
	v_lshl_add_u64 v[204:205], v[138:139], 0, s[4:5]
	v_lshl_add_u64 v[204:205], v[204:205], 0, s[64:65]
	global_load_lds_dwordx4 v[204:205], off
	v_add3_u32 v204, s13, v145, v147
	v_add_u32_e32 v204, v204, v151
	ds_read_b128 v[204:207], v204 offset:12288
	v_add3_u32 v154, s13, v149, v147
	v_add_u32_e32 v154, v154, v152
	ds_read_b128 v[154:157], v154 offset:32768
	v_add3_u32 v158, s13, v149, v147
	v_add_u32_e32 v158, v158, v152
	ds_read_b128 v[158:161], v158 offset:36864
	s_waitcnt lgkmcnt(5)
	v_mfma_f32_32x32x16_bf16 v[114:129], v[192:195], v[162:165], v[114:129]
	v_mfma_f32_32x32x16_bf16 v[98:113], v[192:195], v[208:211], v[98:113]
	v_add3_u32 v192, s13, v145, v147
	v_add_u32_e32 v192, v192, v152
	ds_read_b128 v[192:195], v192
	s_waitcnt lgkmcnt(5)
	v_mfma_f32_32x32x16_bf16 v[82:97], v[196:199], v[162:165], v[82:97]
	v_mfma_f32_32x32x16_bf16 v[66:81], v[196:199], v[208:211], v[66:81]
	v_add3_u32 v196, s13, v145, v147
	v_add_u32_e32 v196, v196, v152
	ds_read_b128 v[196:199], v196 offset:4096
	s_waitcnt lgkmcnt(5)
	v_mfma_f32_32x32x16_bf16 v[50:65], v[200:203], v[162:165], v[50:65]
	v_mfma_f32_32x32x16_bf16 v[34:49], v[200:203], v[208:211], v[34:49]
	v_add3_u32 v200, s13, v145, v147
	v_add_u32_e32 v200, v200, v152
	ds_read_b128 v[200:203], v200 offset:8192
	s_waitcnt lgkmcnt(5)
	v_mfma_f32_32x32x16_bf16 v[18:33], v[204:207], v[162:165], v[18:33]
	v_mfma_f32_32x32x16_bf16 v[2:17], v[204:207], v[208:211], v[2:17]
	v_add3_u32 v204, s13, v145, v147
	v_add_u32_e32 v204, v204, v152
	ds_read_b128 v[204:207], v204 offset:12288
	v_add3_u32 v162, s13, v149, v147
	v_add_u32_e32 v162, v162, v153
	ds_read_b128 v[162:165], v162 offset:32768
	v_add3_u32 v208, s13, v149, v147
	v_add_u32_e32 v208, v208, v153
	ds_read_b128 v[208:211], v208 offset:36864
	s_waitcnt lgkmcnt(5)
	v_mfma_f32_32x32x16_bf16 v[114:129], v[192:195], v[154:157], v[114:129]
	v_mfma_f32_32x32x16_bf16 v[98:113], v[192:195], v[158:161], v[98:113]
	v_add3_u32 v192, s13, v145, v147
	v_add_u32_e32 v192, v192, v153
	ds_read_b128 v[192:195], v192
	s_waitcnt lgkmcnt(5)
	v_mfma_f32_32x32x16_bf16 v[82:97], v[196:199], v[154:157], v[82:97]
	v_mfma_f32_32x32x16_bf16 v[66:81], v[196:199], v[158:161], v[66:81]
	v_add3_u32 v196, s13, v145, v147
	v_add_u32_e32 v196, v196, v153
	ds_read_b128 v[196:199], v196 offset:4096
	s_waitcnt lgkmcnt(5)
	v_mfma_f32_32x32x16_bf16 v[50:65], v[200:203], v[154:157], v[50:65]
	v_mfma_f32_32x32x16_bf16 v[34:49], v[200:203], v[158:161], v[34:49]
	v_add3_u32 v200, s13, v145, v147
	v_add_u32_e32 v200, v200, v153
	ds_read_b128 v[200:203], v200 offset:8192
	s_waitcnt lgkmcnt(5)
	v_mfma_f32_32x32x16_bf16 v[18:33], v[204:207], v[154:157], v[18:33]
	v_mfma_f32_32x32x16_bf16 v[2:17], v[204:207], v[158:161], v[2:17]
	v_add3_u32 v204, s13, v145, v147
	v_add_u32_e32 v204, v204, v153
	ds_read_b128 v[204:207], v204 offset:12288
	s_waitcnt lgkmcnt(3)
	v_mfma_f32_32x32x16_bf16 v[114:129], v[192:195], v[162:165], v[114:129]
	v_mfma_f32_32x32x16_bf16 v[98:113], v[192:195], v[208:211], v[98:113]
	s_waitcnt lgkmcnt(0)
	s_waitcnt vmcnt(0)
	s_barrier
	v_add3_u32 v154, s12, v149, v147
	v_add_u32_e32 v154, v154, v150
	ds_read_b128 v[154:157], v154 offset:32768
	v_add3_u32 v158, s12, v149, v147
	v_add_u32_e32 v158, v158, v150
	ds_read_b128 v[158:161], v158 offset:36864
	v_add3_u32 v192, s12, v145, v147
	v_add_u32_e32 v192, v192, v150
	ds_read_b128 v[192:195], v192
	v_mfma_f32_32x32x16_bf16 v[82:97], v[196:199], v[162:165], v[82:97]
	v_mfma_f32_32x32x16_bf16 v[66:81], v[196:199], v[208:211], v[66:81]
	v_add3_u32 v196, s12, v145, v147
	v_add_u32_e32 v196, v196, v150
	ds_read_b128 v[196:199], v196 offset:4096
	v_mfma_f32_32x32x16_bf16 v[50:65], v[200:203], v[162:165], v[50:65]
	v_mfma_f32_32x32x16_bf16 v[34:49], v[200:203], v[208:211], v[34:49]
	v_add3_u32 v200, s12, v145, v147
	v_add_u32_e32 v200, v200, v150
	ds_read_b128 v[200:203], v200 offset:8192
	v_mfma_f32_32x32x16_bf16 v[18:33], v[204:207], v[162:165], v[18:33]
	v_mfma_f32_32x32x16_bf16 v[2:17], v[204:207], v[208:211], v[2:17]
	v_add3_u32 v204, s12, v145, v147
	v_add_u32_e32 v204, v204, v150
	ds_read_b128 v[204:207], v204 offset:12288
	s_xor_b32 s13, s9, 1
	s_add_u32 s4, s4, 0x80
	s_addc_u32 s5, s5, 0
	s_cmpk_eq_i32 s4, 0x780
	s_cbranch_scc0 .LBB0_155
	s_waitcnt lgkmcnt(0)
	s_andn2_b64 vcc, exec, s[2:3]
	s_lshl_b32 s2, s13, 16
	s_cbranch_vccnz .LBB0_147
	v_add_u32_e32 v136, s8, v141
	s_xor_b32 s3, s2, 0x10000
	v_ashrrev_i32_e32 v137, 31, v136
	v_add_u32_e32 v138, s7, v141
	v_add_u32_e32 v0, s3, v142
	v_lshlrev_b64 v[136:137], 11, v[136:137]
	v_ashrrev_i32_e32 v139, 31, v138
	v_add_u32_e32 v154, 0x8000, v0
	v_readfirstlane_b32 s3, v0
	v_lshlrev_b64 v[138:139], 11, v[138:139]
	v_lshl_add_u64 v[136:137], v[130:131], 0, v[136:137]
	s_mov_b32 m0, s3
	v_readfirstlane_b32 s3, v154
	v_add_u32_e32 v156, 0x2000, v0
	v_lshl_add_u64 v[138:139], v[132:133], 0, v[138:139]
	global_load_lds_dwordx4 v[136:137], off
	s_mov_b32 m0, s3
	s_mov_b64 s[4:5], 0x20000
	v_readfirstlane_b32 s3, v156
	v_add_u32_e32 v156, 0xa000, v0
	global_load_lds_dwordx4 v[138:139], off
	v_lshl_add_u64 v[154:155], v[136:137], 0, s[4:5]
	s_mov_b32 m0, s3
	v_readfirstlane_b32 s3, v156
	v_add_u32_e32 v156, 0x4000, v0
	global_load_lds_dwordx4 v[154:155], off
	v_lshl_add_u64 v[154:155], v[138:139], 0, s[4:5]
	s_mov_b32 m0, s3
	s_mov_b64 s[4:5], 0x40000
	v_readfirstlane_b32 s3, v156
	v_add_u32_e32 v156, 0xc000, v0
	global_load_lds_dwordx4 v[154:155], off
	v_lshl_add_u64 v[154:155], v[136:137], 0, s[4:5]
	s_mov_b32 m0, s3
	v_readfirstlane_b32 s3, v156
	global_load_lds_dwordx4 v[154:155], off
	v_lshl_add_u64 v[154:155], v[138:139], 0, s[4:5]
	s_mov_b32 m0, s3
	s_mov_b64 s[4:5], 0x60000
	global_load_lds_dwordx4 v[154:155], off
	v_add_u32_e32 v154, 0x6000, v0
	v_add_u32_e32 v0, 0xe000, v0
	v_readfirstlane_b32 s3, v154
	v_lshl_add_u64 v[136:137], v[136:137], 0, s[4:5]
	s_mov_b32 m0, s3
	v_readfirstlane_b32 s3, v0
	global_load_lds_dwordx4 v[136:137], off
	v_lshl_add_u64 v[136:137], v[138:139], 0, s[4:5]
	s_mov_b32 m0, s3
	s_nop 0
	global_load_lds_dwordx4 v[136:137], off
	s_branch .LBB0_147

; template <int EPI, int AMAP, int KOFFMODE, int K>
; __device__ __forceinline__ void gemm_phase(unsigned char* smem, const bf16_t* A, int lda, const bf16_t* Bt, int NT, const EpiArgs& ea) {
;     ...
;         f32x16 acc[4][2];
; #pragma unroll
;         for (int i = 0; i < 4; ++i)
; #pragma unroll
;             for (int j = 0; j < 2; ++j)
; #pragma unroll
;                 for (int r = 0; r < 16; ++r) acc[i][j][r] = 0.f;
;         for (int kt = 0; kt < nk; ++kt) {
;             if (kt + 1 < nk) GEMM_DMA(m0, n0, kt + 1, cur ^ 1);
;             else if (have_next) GEMM_DMA(m0n, n0n, 0, cur ^ 1);
;             const unsigned char* Ac = smem + cur * STGB + (wm * 128 + l31) * 128;
;             const unsigned char* Bc = smem + cur * STGB + 32768 + (wn * 64 + l31) * 128;
;             bf16x8 fa[2][4], fb[2][2];
;             fb[0][0] = *(const bf16x8*)(Bc + (((0) ^ yz) & 7) * 16);
;             fb[0][1] = *(const bf16x8*)(Bc + 32 * 128 + (((0) ^ yz) & 7) * 16);
; #pragma unroll
;             for (int i = 0; i < 4; ++i) fa[0][i] = *(const bf16x8*)(Ac + i * 32 * 128 + (((0) ^ yz) & 7) * 16);
; #pragma unroll
;             for (int s = 0; s < 4; ++s) {
;                 if (s < 3) {
;                     const int o_ = (((2 * (s + 1)) ^ yz) & 7) * 16;
;                     fb[(s + 1) & 1][0] = *(const bf16x8*)(Bc + o_);
;                     fb[(s + 1) & 1][1] = *(const bf16x8*)(Bc + 32 * 128 + o_);
; #pragma unroll
;                     for (int i = 0; i < 4; ++i) fa[(s + 1) & 1][i] = *(const bf16x8*)(Ac + i * 32 * 128 + o_);
;                 }
; #pragma unroll
;                 for (int i = 0; i < 4; ++i) {
;                     acc[i][0] = __builtin_amdgcn_mfma_f32_32x32x16_bf16(fa[s & 1][i], fb[s & 1][0], acc[i][0], 0, 0, 0);
;                     acc[i][1] = __builtin_amdgcn_mfma_f32_32x32x16_bf16(fa[s & 1][i], fb[s & 1][1], acc[i][1], 0, 0, 0);
;                 }
;                 __builtin_amdgcn_sched_barrier(0);
;             }
;             if (kt + 1 < nk) asm volatile("s_waitcnt vmcnt(0)" ::: "memory");
;             __builtin_amdgcn_s_barrier();
;             cur ^= 1;
;         }
.LBB0_519:
	v_add_u32_e32 v2, s10, v141
	v_ashrrev_i32_e32 v3, 31, v2
	v_lshlrev_b64 v[2:3], 11, v[2:3]
	v_lshl_add_u64 v[136:137], v[134:135], 0, v[2:3]
	v_add_u32_e32 v2, s11, v141
	v_ashrrev_i32_e32 v3, 31, v2
	v_lshlrev_b64 v[2:3], 11, v[2:3]
	v_lshl_add_u64 v[138:139], v[134:135], 0, v[2:3]
	v_mov_b32_e32 v2, 0
	s_mov_b64 s[4:5], 0
	s_mov_b32 s13, s9
	v_mov_b32_e32 v3, v2
	v_mov_b32_e32 v4, v2
	v_mov_b32_e32 v5, v2
	v_mov_b32_e32 v6, v2
	v_mov_b32_e32 v7, v2
	v_mov_b32_e32 v8, v2
	v_mov_b32_e32 v9, v2
	v_mov_b32_e32 v10, v2
	v_mov_b32_e32 v11, v2
	v_mov_b32_e32 v12, v2
	v_mov_b32_e32 v13, v2
	v_mov_b32_e32 v14, v2
	v_mov_b32_e32 v15, v2
	v_mov_b32_e32 v16, v2
	v_mov_b32_e32 v17, v2
	v_mov_b32_e32 v34, v2
	v_mov_b32_e32 v35, v2
	v_mov_b32_e32 v36, v2
	v_mov_b32_e32 v37, v2
	v_mov_b32_e32 v38, v2
	v_mov_b32_e32 v39, v2
	v_mov_b32_e32 v40, v2
	v_mov_b32_e32 v41, v2
	v_mov_b32_e32 v42, v2
	v_mov_b32_e32 v43, v2
	v_mov_b32_e32 v44, v2
	v_mov_b32_e32 v45, v2
	v_mov_b32_e32 v46, v2
	v_mov_b32_e32 v47, v2
	v_mov_b32_e32 v48, v2
	v_mov_b32_e32 v49, v2
	v_mov_b32_e32 v18, v2
	v_mov_b32_e32 v19, v2
	v_mov_b32_e32 v20, v2
	v_mov_b32_e32 v21, v2
	v_mov_b32_e32 v22, v2
	v_mov_b32_e32 v23, v2
	v_mov_b32_e32 v24, v2
	v_mov_b32_e32 v25, v2
	v_mov_b32_e32 v26, v2
	v_mov_b32_e32 v27, v2
	v_mov_b32_e32 v28, v2
	v_mov_b32_e32 v29, v2
	v_mov_b32_e32 v30, v2
	v_mov_b32_e32 v31, v2
	v_mov_b32_e32 v32, v2
	v_mov_b32_e32 v33, v2
	v_mov_b32_e32 v50, v2
	v_mov_b32_e32 v51, v2
	v_mov_b32_e32 v52, v2
	v_mov_b32_e32 v53, v2
	v_mov_b32_e32 v54, v2
	v_mov_b32_e32 v55, v2
	v_mov_b32_e32 v56, v2
	v_mov_b32_e32 v57, v2
	v_mov_b32_e32 v58, v2
	v_mov_b32_e32 v59, v2
	v_mov_b32_e32 v60, v2
	v_mov_b32_e32 v61, v2
	v_mov_b32_e32 v62, v2
	v_mov_b32_e32 v63, v2
	v_mov_b32_e32 v64, v2
	v_mov_b32_e32 v65, v2
	v_mov_b32_e32 v66, v2
	v_mov_b32_e32 v67, v2
	v_mov_b32_e32 v68, v2
	v_mov_b32_e32 v69, v2
	v_mov_b32_e32 v70, v2
	v_mov_b32_e32 v71, v2
	v_mov_b32_e32 v72, v2
	v_mov_b32_e32 v73, v2
	v_mov_b32_e32 v74, v2
	v_mov_b32_e32 v75, v2
	v_mov_b32_e32 v76, v2
	v_mov_b32_e32 v77, v2
	v_mov_b32_e32 v78, v2
	v_mov_b32_e32 v79, v2
	v_mov_b32_e32 v80, v2
	v_mov_b32_e32 v81, v2
	v_mov_b32_e32 v98, v2
	v_mov_b32_e32 v99, v2
	v_mov_b32_e32 v100, v2
	v_mov_b32_e32 v101, v2
	v_mov_b32_e32 v102, v2
	v_mov_b32_e32 v103, v2
	v_mov_b32_e32 v104, v2
	v_mov_b32_e32 v105, v2
	v_mov_b32_e32 v106, v2
	v_mov_b32_e32 v107, v2
	v_mov_b32_e32 v108, v2
	v_mov_b32_e32 v109, v2
	v_mov_b32_e32 v110, v2
	v_mov_b32_e32 v111, v2
	v_mov_b32_e32 v112, v2
	v_mov_b32_e32 v113, v2
	v_mov_b32_e32 v82, v2
	v_mov_b32_e32 v83, v2
	v_mov_b32_e32 v84, v2
	v_mov_b32_e32 v85, v2
	v_mov_b32_e32 v86, v2
	v_mov_b32_e32 v87, v2
	v_mov_b32_e32 v88, v2
	v_mov_b32_e32 v89, v2
	v_mov_b32_e32 v90, v2
	v_mov_b32_e32 v91, v2
	v_mov_b32_e32 v92, v2
	v_mov_b32_e32 v93, v2
	v_mov_b32_e32 v94, v2
	v_mov_b32_e32 v95, v2
	v_mov_b32_e32 v96, v2
	v_mov_b32_e32 v97, v2
	v_mov_b32_e32 v114, v2
	v_mov_b32_e32 v115, v2
	v_mov_b32_e32 v116, v2
	v_mov_b32_e32 v117, v2
	v_mov_b32_e32 v118, v2
	v_mov_b32_e32 v119, v2
	v_mov_b32_e32 v120, v2
	v_mov_b32_e32 v121, v2
	v_mov_b32_e32 v122, v2
	v_mov_b32_e32 v123, v2
	v_mov_b32_e32 v124, v2
	v_mov_b32_e32 v125, v2
	v_mov_b32_e32 v126, v2
	v_mov_b32_e32 v127, v2
	v_mov_b32_e32 v128, v2
	v_mov_b32_e32 v129, v2
	s_mov_b64 s[20:21], 0x2000080
	s_mov_b64 vcc, 0x200080
	s_mov_b64 s[80:81], 0x2020080
	s_mov_b64 s[68:69], 0x220080
	s_mov_b64 s[88:89], 0x2040080
	s_mov_b64 s[92:93], 0x240080
	s_mov_b64 s[62:63], 0x2060080
	s_mov_b64 s[64:65], 0x260080
	s_lshl_b32 s14, s13, 16
	v_add3_u32 v154, s14, v149, v147
	v_add_u32_e32 v154, v154, v150
	ds_read_b128 v[154:157], v154 offset:32768
	v_add3_u32 v158, s14, v149, v147
	v_add_u32_e32 v158, v158, v150
	ds_read_b128 v[158:161], v158 offset:36864
	v_add3_u32 v192, s14, v145, v147
	v_add_u32_e32 v192, v192, v150
	ds_read_b128 v[192:195], v192
	v_add3_u32 v196, s14, v145, v147
	v_add_u32_e32 v196, v196, v150
	ds_read_b128 v[196:199], v196 offset:4096
	v_add3_u32 v200, s14, v145, v147
	v_add_u32_e32 v200, v200, v150
	ds_read_b128 v[200:203], v200 offset:8192
	v_add3_u32 v204, s14, v145, v147
	v_add_u32_e32 v204, v204, v150
	ds_read_b128 v[204:207], v204 offset:12288
.LBB0_520:
	s_mov_b32 s9, s13
	s_lshl_b32 s13, s9, 16
	s_xor_b32 s12, s13, 0x10000
	v_readfirstlane_b32 s14, v142
	s_nop 0
	s_add_u32 s14, s14, s12
	v_add3_u32 v162, s13, v149, v147
	v_add_u32_e32 v162, v162, v151
	ds_read_b128 v[162:165], v162 offset:32768
	v_add3_u32 v208, s13, v149, v147
	v_add_u32_e32 v208, v208, v151
	ds_read_b128 v[208:211], v208 offset:36864
	s_waitcnt lgkmcnt(5)
	v_mfma_f32_32x32x16_bf16 v[114:129], v[192:195], v[154:157], v[114:129]
	v_mfma_f32_32x32x16_bf16 v[82:97], v[192:195], v[158:161], v[82:97]
	s_mov_b32 m0, s14
	v_lshl_add_u64 v[192:193], v[136:137], 0, s[4:5]
	v_lshl_add_u64 v[192:193], v[192:193], 0, s[20:21]
	global_load_lds_dwordx4 v[192:193], off
	s_add_u32 m0, s14, 0x2000
	v_lshl_add_u64 v[192:193], v[136:137], 0, s[4:5]
	v_lshl_add_u64 v[192:193], v[192:193], 0, s[80:81]
	global_load_lds_dwordx4 v[192:193], off
	v_add3_u32 v192, s13, v145, v147
	v_add_u32_e32 v192, v192, v151
	ds_read_b128 v[192:195], v192
	s_waitcnt lgkmcnt(5)
	v_mfma_f32_32x32x16_bf16 v[98:113], v[196:199], v[154:157], v[98:113]
	v_mfma_f32_32x32x16_bf16 v[66:81], v[196:199], v[158:161], v[66:81]
	s_add_u32 m0, s14, 0x4000
	v_lshl_add_u64 v[196:197], v[136:137], 0, s[4:5]
	v_lshl_add_u64 v[196:197], v[196:197], 0, s[88:89]
	global_load_lds_dwordx4 v[196:197], off
	s_add_u32 m0, s14, 0x6000
	v_lshl_add_u64 v[196:197], v[136:137], 0, s[4:5]
	v_lshl_add_u64 v[196:197], v[196:197], 0, s[62:63]
	global_load_lds_dwordx4 v[196:197], off
	v_add3_u32 v196, s13, v145, v147
	v_add_u32_e32 v196, v196, v151
	ds_read_b128 v[196:199], v196 offset:4096
	s_waitcnt lgkmcnt(5)
; template <int EPI, int AMAP, int KOFFMODE, int K>
; __device__ __forceinline__ void gemm_phase(unsigned char* smem, const bf16_t* A, int lda, const bf16_t* Bt, int NT, const EpiArgs& ea) {
;     ...
;         for (int kt = 0; kt < nk; ++kt) {
;             if (kt + 1 < nk) GEMM_DMA(m0, n0, kt + 1, cur ^ 1);
;             else if (have_next) GEMM_DMA(m0n, n0n, 0, cur ^ 1);
;             const unsigned char* Ac = smem + cur * STGB + (wm * 128 + l31) * 128;
;             const unsigned char* Bc = smem + cur * STGB + 32768 + (wn * 64 + l31) * 128;
;             bf16x8 fa[2][4], fb[2][2];
;             fb[0][0] = *(const bf16x8*)(Bc + (((0) ^ yz) & 7) * 16);
;             fb[0][1] = *(const bf16x8*)(Bc + 32 * 128 + (((0) ^ yz) & 7) * 16);
; #pragma unroll
;             for (int i = 0; i < 4; ++i) fa[0][i] = *(const bf16x8*)(Ac + i * 32 * 128 + (((0) ^ yz) & 7) * 16);
; #pragma unroll
;             for (int s = 0; s < 4; ++s) {
;                 if (s < 3) {
;                     const int o_ = (((2 * (s + 1)) ^ yz) & 7) * 16;
;                     fb[(s + 1) & 1][0] = *(const bf16x8*)(Bc + o_);
;                     fb[(s + 1) & 1][1] = *(const bf16x8*)(Bc + 32 * 128 + o_);
; #pragma unroll
;                     for (int i = 0; i < 4; ++i) fa[(s + 1) & 1][i] = *(const bf16x8*)(Ac + i * 32 * 128 + o_);
;                 }
; #pragma unroll
;                 for (int i = 0; i < 4; ++i) {
;                     acc[i][0] = __builtin_amdgcn_mfma_f32_32x32x16_bf16(fa[s & 1][i], fb[s & 1][0], acc[i][0], 0, 0, 0);
;                     acc[i][1] = __builtin_amdgcn_mfma_f32_32x32x16_bf16(fa[s & 1][i], fb[s & 1][1], acc[i][1], 0, 0, 0);
;                 }
;                 __builtin_amdgcn_sched_barrier(0);
;             }
;             if (kt + 1 < nk) asm volatile("s_waitcnt vmcnt(0)" ::: "memory");
;             __builtin_amdgcn_s_barrier();
;             cur ^= 1;
;         }
	v_mfma_f32_32x32x16_bf16 v[50:65], v[200:203], v[154:157], v[50:65]
	v_mfma_f32_32x32x16_bf16 v[18:33], v[200:203], v[158:161], v[18:33]
	s_add_u32 m0, s14, 0x8000
	v_lshl_add_u64 v[200:201], v[138:139], 0, s[4:5]
	v_lshl_add_u64 v[200:201], v[200:201], 0, vcc
	global_load_lds_dwordx4 v[200:201], off
	s_add_u32 m0, s14, 0xa000
	v_lshl_add_u64 v[200:201], v[138:139], 0, s[4:5]
	v_lshl_add_u64 v[200:201], v[200:201], 0, s[68:69]
	global_load_lds_dwordx4 v[200:201], off
	v_add3_u32 v200, s13, v145, v147
	v_add_u32_e32 v200, v200, v151
	ds_read_b128 v[200:203], v200 offset:8192
	s_waitcnt lgkmcnt(5)
	v_mfma_f32_32x32x16_bf16 v[34:49], v[204:207], v[154:157], v[34:49]
	v_mfma_f32_32x32x16_bf16 v[2:17], v[204:207], v[158:161], v[2:17]
	s_add_u32 m0, s14, 0xc000
	v_lshl_add_u64 v[204:205], v[138:139], 0, s[4:5]
	v_lshl_add_u64 v[204:205], v[204:205], 0, s[92:93]
	global_load_lds_dwordx4 v[204:205], off
	s_add_u32 m0, s14, 0xe000
	v_lshl_add_u64 v[204:205], v[138:139], 0, s[4:5]
	v_lshl_add_u64 v[204:205], v[204:205], 0, s[64:65]
	global_load_lds_dwordx4 v[204:205], off
	v_add3_u32 v204, s13, v145, v147
	v_add_u32_e32 v204, v204, v151
	ds_read_b128 v[204:207], v204 offset:12288
	v_add3_u32 v154, s13, v149, v147
	v_add_u32_e32 v154, v154, v152
	ds_read_b128 v[154:157], v154 offset:32768
	v_add3_u32 v158, s13, v149, v147
	v_add_u32_e32 v158, v158, v152
	ds_read_b128 v[158:161], v158 offset:36864
	s_waitcnt lgkmcnt(5)
	v_mfma_f32_32x32x16_bf16 v[114:129], v[192:195], v[162:165], v[114:129]
	v_mfma_f32_32x32x16_bf16 v[82:97], v[192:195], v[208:211], v[82:97]
	v_add3_u32 v192, s13, v145, v147
	v_add_u32_e32 v192, v192, v152
	ds_read_b128 v[192:195], v192
	s_waitcnt lgkmcnt(5)
	v_mfma_f32_32x32x16_bf16 v[98:113], v[196:199], v[162:165], v[98:113]
	v_mfma_f32_32x32x16_bf16 v[66:81], v[196:199], v[208:211], v[66:81]
	v_add3_u32 v196, s13, v145, v147
	v_add_u32_e32 v196, v196, v152
	ds_read_b128 v[196:199], v196 offset:4096
	s_waitcnt lgkmcnt(5)
	v_mfma_f32_32x32x16_bf16 v[50:65], v[200:203], v[162:165], v[50:65]
	v_mfma_f32_32x32x16_bf16 v[18:33], v[200:203], v[208:211], v[18:33]
	v_add3_u32 v200, s13, v145, v147
	v_add_u32_e32 v200, v200, v152
	ds_read_b128 v[200:203], v200 offset:8192
	s_waitcnt lgkmcnt(5)
	v_mfma_f32_32x32x16_bf16 v[34:49], v[204:207], v[162:165], v[34:49]
	v_mfma_f32_32x32x16_bf16 v[2:17], v[204:207], v[208:211], v[2:17]
	v_add3_u32 v204, s13, v145, v147
	v_add_u32_e32 v204, v204, v152
	ds_read_b128 v[204:207], v204 offset:12288
	v_add3_u32 v162, s13, v149, v147
	v_add_u32_e32 v162, v162, v153
	ds_read_b128 v[162:165], v162 offset:32768
	v_add3_u32 v208, s13, v149, v147
	v_add_u32_e32 v208, v208, v153
	ds_read_b128 v[208:211], v208 offset:36864
	s_waitcnt lgkmcnt(5)
	v_mfma_f32_32x32x16_bf16 v[114:129], v[192:195], v[154:157], v[114:129]
	v_mfma_f32_32x32x16_bf16 v[82:97], v[192:195], v[158:161], v[82:97]
	v_add3_u32 v192, s13, v145, v147
	v_add_u32_e32 v192, v192, v153
	ds_read_b128 v[192:195], v192
	s_waitcnt lgkmcnt(5)
	v_mfma_f32_32x32x16_bf16 v[98:113], v[196:199], v[154:157], v[98:113]
	v_mfma_f32_32x32x16_bf16 v[66:81], v[196:199], v[158:161], v[66:81]
	v_add3_u32 v196, s13, v145, v147
	v_add_u32_e32 v196, v196, v153
	ds_read_b128 v[196:199], v196 offset:4096
	s_waitcnt lgkmcnt(5)
	v_mfma_f32_32x32x16_bf16 v[50:65], v[200:203], v[154:157], v[50:65]
	v_mfma_f32_32x32x16_bf16 v[18:33], v[200:203], v[158:161], v[18:33]
	v_add3_u32 v200, s13, v145, v147
	v_add_u32_e32 v200, v200, v153
	ds_read_b128 v[200:203], v200 offset:8192
	s_waitcnt lgkmcnt(5)
	v_mfma_f32_32x32x16_bf16 v[34:49], v[204:207], v[154:157], v[34:49]
	v_mfma_f32_32x32x16_bf16 v[2:17], v[204:207], v[158:161], v[2:17]
	v_add3_u32 v204, s13, v145, v147
	v_add_u32_e32 v204, v204, v153
	ds_read_b128 v[204:207], v204 offset:12288
	s_waitcnt lgkmcnt(3)
	v_mfma_f32_32x32x16_bf16 v[114:129], v[192:195], v[162:165], v[114:129]
	v_mfma_f32_32x32x16_bf16 v[82:97], v[192:195], v[208:211], v[82:97]
	s_waitcnt lgkmcnt(0)
	s_waitcnt vmcnt(0)
	s_barrier
	v_add3_u32 v154, s12, v149, v147
	v_add_u32_e32 v154, v154, v150
	ds_read_b128 v[154:157], v154 offset:32768
	v_add3_u32 v158, s12, v149, v147
	v_add_u32_e32 v158, v158, v150
	ds_read_b128 v[158:161], v158 offset:36864
	v_add3_u32 v192, s12, v145, v147
	v_add_u32_e32 v192, v192, v150
	ds_read_b128 v[192:195], v192
	v_mfma_f32_32x32x16_bf16 v[98:113], v[196:199], v[162:165], v[98:113]
	v_mfma_f32_32x32x16_bf16 v[66:81], v[196:199], v[208:211], v[66:81]
	v_add3_u32 v196, s12, v145, v147
	v_add_u32_e32 v196, v196, v150
	ds_read_b128 v[196:199], v196 offset:4096
	v_mfma_f32_32x32x16_bf16 v[50:65], v[200:203], v[162:165], v[50:65]
	v_mfma_f32_32x32x16_bf16 v[18:33], v[200:203], v[208:211], v[18:33]
	v_add3_u32 v200, s12, v145, v147
	v_add_u32_e32 v200, v200, v150
	ds_read_b128 v[200:203], v200 offset:8192
	v_mfma_f32_32x32x16_bf16 v[34:49], v[204:207], v[162:165], v[34:49]
	v_mfma_f32_32x32x16_bf16 v[2:17], v[204:207], v[208:211], v[2:17]
	v_add3_u32 v204, s12, v145, v147
	v_add_u32_e32 v204, v204, v150
	ds_read_b128 v[204:207], v204 offset:12288
	s_xor_b32 s13, s9, 1
	s_add_u32 s4, s4, 0x80
	s_addc_u32 s5, s5, 0
	s_cmpk_eq_i32 s4, 0x780
	s_cbranch_scc0 .LBB0_520
	s_waitcnt lgkmcnt(0)
	s_andn2_b64 vcc, exec, s[2:3]
	s_lshl_b32 s2, s13, 16
	s_mov_b64 s[62:63], 0x80
	s_mov_b64 s[64:65], 0x10000
	s_mov_b32 s92, 0x3e38aa3b
	s_cbranch_vccnz .LBB0_523
	v_add_u32_e32 v136, s8, v141
	s_xor_b32 s3, s2, 0x10000
	v_ashrrev_i32_e32 v137, 31, v136
	v_add_u32_e32 v138, s7, v141
	v_add_u32_e32 v0, s3, v142
	v_lshlrev_b64 v[136:137], 11, v[136:137]
	v_ashrrev_i32_e32 v139, 31, v138
	v_add_u32_e32 v154, 0x8000, v0
	v_readfirstlane_b32 s3, v0
	v_lshlrev_b64 v[138:139], 11, v[138:139]
	v_lshl_add_u64 v[136:137], v[130:131], 0, v[136:137]
	s_mov_b32 m0, s3
	v_readfirstlane_b32 s3, v154
	v_add_u32_e32 v156, 0x2000, v0
	v_lshl_add_u64 v[138:139], v[132:133], 0, v[138:139]
	global_load_lds_dwordx4 v[136:137], off
	s_mov_b32 m0, s3
	s_mov_b64 s[4:5], 0x20000
	v_readfirstlane_b32 s3, v156
	v_add_u32_e32 v156, 0xa000, v0
	global_load_lds_dwordx4 v[138:139], off
	v_lshl_add_u64 v[154:155], v[136:137], 0, s[4:5]
	s_mov_b32 m0, s3
	v_readfirstlane_b32 s3, v156
	v_add_u32_e32 v156, 0x4000, v0
	global_load_lds_dwordx4 v[154:155], off
	v_lshl_add_u64 v[154:155], v[138:139], 0, s[4:5]
	s_mov_b32 m0, s3
	s_mov_b64 s[4:5], 0x40000
	v_readfirstlane_b32 s3, v156
	v_add_u32_e32 v156, 0xc000, v0
	global_load_lds_dwordx4 v[154:155], off
	v_lshl_add_u64 v[154:155], v[136:137], 0, s[4:5]
	s_mov_b32 m0, s3
	v_readfirstlane_b32 s3, v156
	global_load_lds_dwordx4 v[154:155], off
	v_lshl_add_u64 v[154:155], v[138:139], 0, s[4:5]
	s_mov_b32 m0, s3
	s_mov_b64 s[4:5], 0x60000
	global_load_lds_dwordx4 v[154:155], off
	v_add_u32_e32 v154, 0x6000, v0
	v_add_u32_e32 v0, 0xe000, v0
	v_readfirstlane_b32 s3, v154
	v_lshl_add_u64 v[136:137], v[136:137], 0, s[4:5]
	s_mov_b32 m0, s3
	v_readfirstlane_b32 s3, v0
	global_load_lds_dwordx4 v[136:137], off
	v_lshl_add_u64 v[136:137], v[138:139], 0, s[4:5]
	s_mov_b32 m0, s3
	s_nop 0
	global_load_lds_dwordx4 v[136:137], off
